# PREP: gates_tiles K-loop with 5-deep rolling operand prefetch (was 32 dependent round trips per tile); ret_kv staging loads issued together
# baseline (speedup 1.0000x reference)
; #define LAS __attribute__((address_space(3)))
; __device__ __forceinline__ void ret_stage(const Frame& F, int b, int h, int n, bool full, float lg) {
;     LAS unsigned char* L = F.lds;
;     const int tk = F.tid >> 2, part = F.tid & 3;
;     const size_t rowoff = (((size_t)b * 4 + h) * S + n * 128 + tk) * 64 + part * 16;
;     const u32x4* kp = (const u32x4*)((const bf16*)(F.ws + WS_PRK) + rowoff);
;     const u32x4* vp = (const u32x4*)((const bf16*)(F.ws + WS_PRV) + rowoff);
;     const u32x4 k0 = kp[0], k1 = kp[1], v0 = vp[0], v1 = vp[1];
;     if (full) { const u32x4* qp = (const u32x4*)((const bf16*)(F.ws + WS_PRQ) + rowoff);
;         const u32x4 q0 = qp[0], q1 = qp[1];
;         *(LAS u32x4*)(L + RL_Q + tk * 128 + part * 32) = q0; *(LAS u32x4*)(L + RL_Q + tk * 128 + part * 32 + 16) = q1;
;         *(LAS u32x4*)(L + RL_K + tk * 128 + part * 32) = k0; *(LAS u32x4*)(L + RL_K + tk * 128 + part * 32 + 16) = k1; }
;     const float kd = expf((float)(127 - tk) * lg);
;     const unsigned kw[8] = {k0.x, k0.y, k0.z, k0.w, k1.x, k1.y, k1.z, k1.w}, vw[8] = {v0.x, v0.y, v0.z, v0.w, v1.x, v1.y, v1.z, v1.w};
; #pragma unroll
;     for (int i = 0; i < 8; ++i) { const int d = part * 16 + 2 * i;
;         if (!full) { const unsigned pk = cvt_pk_bf16(bf2f((unsigned short)(kw[i] & 0xffffu)) * kd, bf2f((unsigned short)(kw[i] >> 16)) * kd);
;             *(LAS unsigned short*)(L + RL_KT + (d * 128 + tk) * 2) = (unsigned short)(pk & 0xffffu); *(LAS unsigned short*)(L + RL_KT + ((d + 1) * 128 + tk) * 2) = (unsigned short)(pk >> 16); }
;         *(LAS unsigned short*)(L + RL_VT + (d * 128 + tk) * 2) = (unsigned short)(vw[i] & 0xffffu); *(LAS unsigned short*)(L + RL_VT + ((d + 1) * 128 + tk) * 2) = (unsigned short)(vw[i] >> 16); }
; }
; __device__ __forceinline__ void ret_kv_unit(const Frame& F, int unit) {
;     const int n = unit & 15, h = (unit >> 4) & 3, b = unit >> 6;
;     const float lg = c_log_gamma[h];
;     LAS unsigned char* L = F.lds;
;     __syncthreads();
;     ret_stage(F, b, h, n, false, lg);
;     __syncthreads();
;     const int fr = F.lane & 15, fq = F.lane >> 4, dtile = F.wave >> 1, et0 = (F.wave & 1) * 2;
;     f32x4 a0 = {0.f, 0.f, 0.f, 0.f}, a1 = {0.f, 0.f, 0.f, 0.f};
; #pragma unroll
;     for (int ks = 0; ks < 4; ++ks) {
;         const bf16x8 a = *(const LAS bf16x8*)(L + RL_KT + ((16 * dtile + fr) * 128 + 32 * ks + fq * 8) * 2);
.LBB0_1335:
	s_bfe_u32 s6, s4, 0x20004
	s_and_b32 s5, s4, 15
	s_ashr_i32 s26, s4, 6
	s_lshl_b32 s7, s6, 2
	s_getpc_b64 s[10:11]
	s_add_u32 s10, s10, c_log_gamma@rel32@lo+4
	s_addc_u32 s11, s11, c_log_gamma@rel32@hi+12
	s_ashr_i32 s27, s26, 31
	s_load_dword s7, s[10:11], s7 offset:0x0
	s_lshl_b64 s[10:11], s[26:27], 13
	s_lshl_b32 s9, s6, 11
	s_lshl_b32 s30, s5, 7
	s_or_b32 s9, s10, s9
	s_or_b32 s10, s9, s30
	v_lshl_add_u64 v[20:21], s[10:11], 0, v[2:3]
	v_lshlrev_b64 v[20:21], 7, v[20:21]
	v_lshl_or_b32 v20, v4, 1, v20
	s_waitcnt vmcnt(20)
	v_lshl_add_u64 v[24:25], s[0:1], 0, v[20:21]
	s_waitcnt lgkmcnt(0)
	s_barrier
	s_waitcnt vmcnt(16)
	v_lshl_add_u64 v[32:33], s[14:15], 0, v[20:21]
	global_load_dwordx4 v[20:23], v[24:25], off offset:16
	s_nop 0
	global_load_dwordx4 v[24:27], v[24:25], off
	global_load_dwordx4 v[40:43], v[32:33], off
	s_nop 0
	global_load_dwordx4 v[44:47], v[32:33], off offset:16
	v_mul_f32_e32 v19, s7, v8
	v_mul_f32_e32 v28, 0x3fb8aa3b, v19
	v_fma_f32 v29, v19, s17, -v28
	v_rndne_f32_e32 v30, v28
	v_fmac_f32_e32 v29, 0x32a5705f, v19
	v_sub_f32_e32 v28, v28, v30
	v_add_f32_e32 v28, v28, v29
	v_exp_f32_e32 v28, v28
	v_cvt_i32_f32_e32 v29, v30
	v_cmp_ngt_f32_e32 vcc, s21, v19
	s_lshl_b64 s[10:11], s[26:27], 6
	s_lshl_b32 s6, s6, 4
	v_ldexp_f32 v28, v28, v29
	v_cndmask_b32_e32 v28, 0, v28, vcc
	v_cmp_nlt_f32_e32 vcc, s22, v19
	s_or_b32 s6, s10, s6
	s_or_b32 s10, s6, s5
	v_cndmask_b32_e32 v19, v230, v28, vcc
	s_lshl_b64 s[6:7], s[10:11], 14
	s_add_i32 s4, s4, s76
	s_cmpk_gt_i32 s4, 0x1ff
	s_waitcnt vmcnt(2)
	v_lshlrev_b32_e32 v28, 16, v24
	v_and_b32_e32 v24, 0xffff0000, v24
	v_mul_f32_e32 v24, v19, v24
	v_mul_f32_e32 v28, v19, v28
	v_cvt_pk_bf16_f32 v24, v28, v24
	ds_write_b16 v9, v24 offset:32768
	ds_write_b16_d16_hi v9, v24 offset:33024
	v_lshlrev_b32_e32 v24, 16, v25
	v_mul_f32_e32 v24, v19, v24
	v_and_b32_e32 v25, 0xffff0000, v25
	v_mul_f32_e32 v25, v19, v25
	v_cvt_pk_bf16_f32 v24, v24, v25
	v_and_b32_e32 v25, 0xffff0000, v26
	v_mul_f32_e32 v25, v19, v25
	s_waitcnt vmcnt(1)
	ds_write_b16 v9, v40 offset:49152
	ds_write_b16_d16_hi v9, v40 offset:49408
	ds_write_b16 v9, v24 offset:33280
	ds_write_b16_d16_hi v9, v24 offset:33536
	ds_write_b16 v9, v41 offset:49664
	ds_write_b16_d16_hi v9, v41 offset:49920
	v_lshlrev_b32_e32 v24, 16, v26
	v_mul_f32_e32 v24, v19, v24
	v_cvt_pk_bf16_f32 v24, v24, v25
	ds_write_b16 v9, v24 offset:33792
	ds_write_b16_d16_hi v9, v24 offset:34048
	ds_write_b16 v9, v42 offset:50176
	ds_write_b16_d16_hi v9, v42 offset:50432
	v_lshlrev_b32_e32 v24, 16, v27
	v_mul_f32_e32 v24, v19, v24
	v_and_b32_e32 v25, 0xffff0000, v27
	v_mul_f32_e32 v25, v19, v25
	v_cvt_pk_bf16_f32 v24, v24, v25
	ds_write_b16 v9, v24 offset:34304
	ds_write_b16_d16_hi v9, v24 offset:34560
	ds_write_b16 v9, v43 offset:50688
	ds_write_b16_d16_hi v9, v43 offset:50944
	v_lshlrev_b32_e32 v24, 16, v20
	v_and_b32_e32 v20, 0xffff0000, v20
	v_mul_f32_e32 v20, v19, v20
	v_mul_f32_e32 v24, v19, v24
	v_cvt_pk_bf16_f32 v20, v24, v20
	ds_write_b16 v9, v20 offset:34816
	ds_write_b16_d16_hi v9, v20 offset:35072
	s_waitcnt vmcnt(0)
	ds_write_b16 v9, v44 offset:51200
	ds_write_b16_d16_hi v9, v44 offset:51456
	v_lshlrev_b32_e32 v20, 16, v21
	v_mul_f32_e32 v20, v19, v20
	v_and_b32_e32 v21, 0xffff0000, v21
	v_mul_f32_e32 v21, v19, v21
	v_cvt_pk_bf16_f32 v20, v20, v21
	ds_write_b16 v9, v20 offset:35328
	ds_write_b16_d16_hi v9, v20 offset:35584
	ds_write_b16 v9, v45 offset:51712
	ds_write_b16_d16_hi v9, v45 offset:51968
	v_lshlrev_b32_e32 v20, 16, v22
	v_mul_f32_e32 v20, v19, v20
	v_and_b32_e32 v21, 0xffff0000, v22
	v_mul_f32_e32 v21, v19, v21
	v_cvt_pk_bf16_f32 v20, v20, v21
	ds_write_b16 v9, v20 offset:35840
	ds_write_b16_d16_hi v9, v20 offset:36096
	ds_write_b16 v9, v46 offset:52224
	ds_write_b16_d16_hi v9, v46 offset:52480
	v_lshlrev_b32_e32 v20, 16, v23
	v_and_b32_e32 v21, 0xffff0000, v23
	v_mul_f32_e32 v20, v19, v20
	v_mul_f32_e32 v19, v19, v21
	v_cvt_pk_bf16_f32 v19, v20, v19
	ds_write_b16 v9, v19 offset:36352
	ds_write_b16_d16_hi v9, v19 offset:36608
	ds_write_b16 v9, v47 offset:52736
	ds_write_b16_d16_hi v9, v47 offset:52992
	s_waitcnt lgkmcnt(0)
	s_barrier
	ds_read_b128 v[20:23], v10 offset:32768
	ds_read_b128 v[24:27], v11 offset:49152
	ds_read_b128 v[28:31], v12 offset:49152
	s_waitcnt lgkmcnt(1)
	v_mfma_f32_16x16x32_bf16 v[24:27], v[20:23], v[24:27], 0
	s_waitcnt lgkmcnt(0)
	v_mfma_f32_16x16x32_bf16 v[20:23], v[20:23], v[28:31], 0
	ds_read_b128 v[28:31], v10 offset:32832
	ds_read_b128 v[32:35], v13 offset:49152
	ds_read_b128 v[36:39], v14 offset:49152
	s_waitcnt lgkmcnt(1)
	v_mfma_f32_16x16x32_bf16 v[24:27], v[28:31], v[32:35], v[24:27]
	s_waitcnt lgkmcnt(0)
	v_mfma_f32_16x16x32_bf16 v[20:23], v[28:31], v[36:39], v[20:23]
	ds_read_b128 v[28:31], v10 offset:32896
	ds_read_b128 v[32:35], v15 offset:49152
	ds_read_b128 v[36:39], v16 offset:49152
	s_waitcnt lgkmcnt(1)
	v_mfma_f32_16x16x32_bf16 v[24:27], v[28:31], v[32:35], v[24:27]
	s_waitcnt lgkmcnt(0)
	v_mfma_f32_16x16x32_bf16 v[20:23], v[28:31], v[36:39], v[20:23]
	ds_read_b128 v[28:31], v10 offset:32960
	ds_read_b128 v[32:35], v17 offset:49152
	ds_read_b128 v[36:39], v18 offset:49152
	s_waitcnt lgkmcnt(1)
	v_mfma_f32_16x16x32_bf16 v[24:27], v[28:31], v[32:35], v[24:27]
	s_waitcnt lgkmcnt(0)
	v_mfma_f32_16x16x32_bf16 v[20:23], v[28:31], v[36:39], v[20:23]
	v_lshl_add_u64 v[28:29], v[6:7], 0, s[6:7]
	s_nop 4
	global_store_dword v[28:29], v24, off
	s_nop 0
	global_store_dword v[28:29], v20, off offset:64
	global_store_dword v[28:29], v25, off offset:256
	global_store_dword v[28:29], v21, off offset:320
	global_store_dword v[28:29], v26, off offset:512
	global_store_dword v[28:29], v22, off offset:576
	global_store_dword v[28:29], v27, off offset:768
	global_store_dword v[28:29], v23, off offset:832
	v_mov_b32_e32 v24, v5
	s_cbranch_scc0 .LBB0_1335

; __device__ __forceinline__ void gates_tiles(const Frame& F, int l, int wg0) {
;     ...
;     for (int rt = gw; rt < T / 16; rt += NGW) {
;         f32x4 a0 = {0.f, 0.f, 0.f, 0.f}, a1 = {0.f, 0.f, 0.f, 0.f};
;         const bf16* ap = H + (size_t)(16 * rt + fr) * D + 8 * fq; const bf16* bp = WG + (size_t)fr * D + 8 * fq;
; #pragma unroll 8
;         for (int ks = 0; ks < 32; ++ks) { const bf16x8 a = *(const bf16x8*)(ap + 32 * ks), b0 = *(const bf16x8*)(bp + 32 * ks), b1 = *(const bf16x8*)(bp + 16 * D + 32 * ks);
;             a0 = __builtin_amdgcn_mfma_f32_16x16x32_bf16(b0, a, a0, 0, 0, 0); a1 = __builtin_amdgcn_mfma_f32_16x16x32_bf16(b1, a, a1, 0, 0, 0); }
.LBB0_1340:
	v_add_co_u32_e32 v38, vcc, 0x4000000, v18
	s_nop 1
	v_addc_co_u32_e32 v39, vcc, 0, v19, vcc
	v_add_co_u32_e32 v20, vcc, 0x1e00000, v16
	s_nop 1
	v_addc_co_u32_e32 v21, vcc, 0, v17, vcc
	v_add_co_u32_e32 v22, vcc, 0x1e08000, v16
	s_nop 1
	v_addc_co_u32_e32 v23, vcc, 0, v17, vcc
	global_load_dwordx4 v[40:43], v[38:39], off
	global_load_dwordx4 v[44:47], v[20:21], off
	global_load_dwordx4 v[48:51], v[22:23], off
	global_load_dwordx4 v[52:55], v[38:39], off offset:64
	global_load_dwordx4 v[62:65], v[20:21], off offset:64
	global_load_dwordx4 v[70:73], v[22:23], off offset:64
	global_load_dwordx4 v[82:85], v[38:39], off offset:128
	global_load_dwordx4 v[86:89], v[20:21], off offset:128
	global_load_dwordx4 v[94:97], v[22:23], off offset:128
	global_load_dwordx4 v[102:105], v[38:39], off offset:192
	global_load_dwordx4 v[130:133], v[20:21], off offset:192
	global_load_dwordx4 v[134:137], v[22:23], off offset:192
	global_load_dwordx4 v[138:141], v[38:39], off offset:256
	global_load_dwordx4 v[142:145], v[20:21], off offset:256
	global_load_dwordx4 v[148:151], v[22:23], off offset:256
	s_waitcnt vmcnt(12)
	v_mfma_f32_16x16x32_bf16 v[6:9], v[44:47], v[40:43], v[6:9]
	v_mfma_f32_16x16x32_bf16 v[2:5], v[48:51], v[40:43], v[2:5]
	global_load_dwordx4 v[40:43], v[38:39], off offset:320
	global_load_dwordx4 v[44:47], v[20:21], off offset:320
	global_load_dwordx4 v[48:51], v[22:23], off offset:320
	s_waitcnt vmcnt(12)
	v_mfma_f32_16x16x32_bf16 v[6:9], v[62:65], v[52:55], v[6:9]
	v_mfma_f32_16x16x32_bf16 v[2:5], v[70:73], v[52:55], v[2:5]
	global_load_dwordx4 v[52:55], v[38:39], off offset:384
	global_load_dwordx4 v[62:65], v[20:21], off offset:384
	global_load_dwordx4 v[70:73], v[22:23], off offset:384
	s_waitcnt vmcnt(12)
	v_mfma_f32_16x16x32_bf16 v[6:9], v[86:89], v[82:85], v[6:9]
	v_mfma_f32_16x16x32_bf16 v[2:5], v[94:97], v[82:85], v[2:5]
	global_load_dwordx4 v[82:85], v[38:39], off offset:448
	global_load_dwordx4 v[86:89], v[20:21], off offset:448
	global_load_dwordx4 v[94:97], v[22:23], off offset:448
	s_waitcnt vmcnt(12)
	v_mfma_f32_16x16x32_bf16 v[6:9], v[130:133], v[102:105], v[6:9]
	v_mfma_f32_16x16x32_bf16 v[2:5], v[134:137], v[102:105], v[2:5]
	global_load_dwordx4 v[102:105], v[38:39], off offset:512
	global_load_dwordx4 v[130:133], v[20:21], off offset:512
	global_load_dwordx4 v[134:137], v[22:23], off offset:512
	s_waitcnt vmcnt(12)
	v_mfma_f32_16x16x32_bf16 v[6:9], v[142:145], v[138:141], v[6:9]
	v_mfma_f32_16x16x32_bf16 v[2:5], v[148:151], v[138:141], v[2:5]
	global_load_dwordx4 v[138:141], v[38:39], off offset:576
	global_load_dwordx4 v[142:145], v[20:21], off offset:576
	global_load_dwordx4 v[148:151], v[22:23], off offset:576
	s_waitcnt vmcnt(12)
	v_mfma_f32_16x16x32_bf16 v[6:9], v[44:47], v[40:43], v[6:9]
	v_mfma_f32_16x16x32_bf16 v[2:5], v[48:51], v[40:43], v[2:5]
	global_load_dwordx4 v[40:43], v[38:39], off offset:640
	global_load_dwordx4 v[44:47], v[20:21], off offset:640
	global_load_dwordx4 v[48:51], v[22:23], off offset:640
	s_waitcnt vmcnt(12)
	v_mfma_f32_16x16x32_bf16 v[6:9], v[62:65], v[52:55], v[6:9]
	v_mfma_f32_16x16x32_bf16 v[2:5], v[70:73], v[52:55], v[2:5]
	global_load_dwordx4 v[52:55], v[38:39], off offset:704
	global_load_dwordx4 v[62:65], v[20:21], off offset:704
	global_load_dwordx4 v[70:73], v[22:23], off offset:704
	s_waitcnt vmcnt(12)
	v_mfma_f32_16x16x32_bf16 v[6:9], v[86:89], v[82:85], v[6:9]
	v_mfma_f32_16x16x32_bf16 v[2:5], v[94:97], v[82:85], v[2:5]
	global_load_dwordx4 v[82:85], v[38:39], off offset:768
	global_load_dwordx4 v[86:89], v[20:21], off offset:768
	global_load_dwordx4 v[94:97], v[22:23], off offset:768
	s_waitcnt vmcnt(12)
	v_mfma_f32_16x16x32_bf16 v[6:9], v[130:133], v[102:105], v[6:9]
	v_mfma_f32_16x16x32_bf16 v[2:5], v[134:137], v[102:105], v[2:5]
	global_load_dwordx4 v[102:105], v[38:39], off offset:832
	global_load_dwordx4 v[130:133], v[20:21], off offset:832
	global_load_dwordx4 v[134:137], v[22:23], off offset:832
	s_waitcnt vmcnt(12)
	v_mfma_f32_16x16x32_bf16 v[6:9], v[142:145], v[138:141], v[6:9]
	v_mfma_f32_16x16x32_bf16 v[2:5], v[148:151], v[138:141], v[2:5]
	global_load_dwordx4 v[138:141], v[38:39], off offset:896
	global_load_dwordx4 v[142:145], v[20:21], off offset:896
	global_load_dwordx4 v[148:151], v[22:23], off offset:896
	s_waitcnt vmcnt(12)
	v_mfma_f32_16x16x32_bf16 v[6:9], v[44:47], v[40:43], v[6:9]
	v_mfma_f32_16x16x32_bf16 v[2:5], v[48:51], v[40:43], v[2:5]
	global_load_dwordx4 v[40:43], v[38:39], off offset:960
	global_load_dwordx4 v[44:47], v[20:21], off offset:960
	global_load_dwordx4 v[48:51], v[22:23], off offset:960
	s_waitcnt vmcnt(12)
	v_mfma_f32_16x16x32_bf16 v[6:9], v[62:65], v[52:55], v[6:9]
	v_mfma_f32_16x16x32_bf16 v[2:5], v[70:73], v[52:55], v[2:5]
	global_load_dwordx4 v[52:55], v[38:39], off offset:1024
	global_load_dwordx4 v[62:65], v[20:21], off offset:1024
	global_load_dwordx4 v[70:73], v[22:23], off offset:1024
	s_waitcnt vmcnt(12)
	v_mfma_f32_16x16x32_bf16 v[6:9], v[86:89], v[82:85], v[6:9]
	v_mfma_f32_16x16x32_bf16 v[2:5], v[94:97], v[82:85], v[2:5]
	global_load_dwordx4 v[82:85], v[38:39], off offset:1088
	global_load_dwordx4 v[86:89], v[20:21], off offset:1088
	global_load_dwordx4 v[94:97], v[22:23], off offset:1088
	s_waitcnt vmcnt(12)
	v_mfma_f32_16x16x32_bf16 v[6:9], v[130:133], v[102:105], v[6:9]
	v_mfma_f32_16x16x32_bf16 v[2:5], v[134:137], v[102:105], v[2:5]
	global_load_dwordx4 v[102:105], v[38:39], off offset:1152
	global_load_dwordx4 v[130:133], v[20:21], off offset:1152
	global_load_dwordx4 v[134:137], v[22:23], off offset:1152
	s_waitcnt vmcnt(12)
; __device__ __forceinline__ float sigmoidf_(float x) { return 1.f / (1.f + expf(-x)); }
; __device__ __forceinline__ void gates_tiles(const Frame& F, int l, int wg0) {
;     ...
;     for (int rt = gw; rt < T / 16; rt += NGW) {
;         f32x4 a0 = {0.f, 0.f, 0.f, 0.f}, a1 = {0.f, 0.f, 0.f, 0.f};
;         const bf16* ap = H + (size_t)(16 * rt + fr) * D + 8 * fq; const bf16* bp = WG + (size_t)fr * D + 8 * fq;
; #pragma unroll 8
;         for (int ks = 0; ks < 32; ++ks) { const bf16x8 a = *(const bf16x8*)(ap + 32 * ks), b0 = *(const bf16x8*)(bp + 32 * ks), b1 = *(const bf16x8*)(bp + 16 * D + 32 * ks);
;             a0 = __builtin_amdgcn_mfma_f32_16x16x32_bf16(b0, a, a0, 0, 0, 0); a1 = __builtin_amdgcn_mfma_f32_16x16x32_bf16(b1, a, a1, 0, 0, 0); }
;         float* ng = (float*)(F.ws + WS_NG) + (size_t)(16 * rt + fr) * 24;
; #pragma unroll
;         for (int j = 0; j < 4; ++j) { ng[4 * fq + j] = sigmoidf_(a0[j]); if (fq < 2) ng[16 + 4 * fq + j] = sigmoidf_(a1[j]); }
	v_mfma_f32_16x16x32_bf16 v[6:9], v[142:145], v[138:141], v[6:9]
	v_mfma_f32_16x16x32_bf16 v[2:5], v[148:151], v[138:141], v[2:5]
	global_load_dwordx4 v[138:141], v[38:39], off offset:1216
	global_load_dwordx4 v[142:145], v[20:21], off offset:1216
	global_load_dwordx4 v[148:151], v[22:23], off offset:1216
	s_waitcnt vmcnt(12)
	v_mfma_f32_16x16x32_bf16 v[6:9], v[44:47], v[40:43], v[6:9]
	v_mfma_f32_16x16x32_bf16 v[2:5], v[48:51], v[40:43], v[2:5]
	global_load_dwordx4 v[40:43], v[38:39], off offset:1280
	global_load_dwordx4 v[44:47], v[20:21], off offset:1280
	global_load_dwordx4 v[48:51], v[22:23], off offset:1280
	s_waitcnt vmcnt(12)
	v_mfma_f32_16x16x32_bf16 v[6:9], v[62:65], v[52:55], v[6:9]
	v_mfma_f32_16x16x32_bf16 v[2:5], v[70:73], v[52:55], v[2:5]
	global_load_dwordx4 v[52:55], v[38:39], off offset:1344
	global_load_dwordx4 v[62:65], v[20:21], off offset:1344
	global_load_dwordx4 v[70:73], v[22:23], off offset:1344
	s_waitcnt vmcnt(12)
	v_mfma_f32_16x16x32_bf16 v[6:9], v[86:89], v[82:85], v[6:9]
	v_mfma_f32_16x16x32_bf16 v[2:5], v[94:97], v[82:85], v[2:5]
	global_load_dwordx4 v[82:85], v[38:39], off offset:1408
	global_load_dwordx4 v[86:89], v[20:21], off offset:1408
	global_load_dwordx4 v[94:97], v[22:23], off offset:1408
	s_waitcnt vmcnt(12)
	v_mfma_f32_16x16x32_bf16 v[6:9], v[130:133], v[102:105], v[6:9]
	v_mfma_f32_16x16x32_bf16 v[2:5], v[134:137], v[102:105], v[2:5]
	global_load_dwordx4 v[102:105], v[38:39], off offset:1472
	global_load_dwordx4 v[130:133], v[20:21], off offset:1472
	global_load_dwordx4 v[134:137], v[22:23], off offset:1472
	s_waitcnt vmcnt(12)
	v_mfma_f32_16x16x32_bf16 v[6:9], v[142:145], v[138:141], v[6:9]
	v_mfma_f32_16x16x32_bf16 v[2:5], v[148:151], v[138:141], v[2:5]
	global_load_dwordx4 v[138:141], v[38:39], off offset:1536
	global_load_dwordx4 v[142:145], v[20:21], off offset:1536
	global_load_dwordx4 v[148:151], v[22:23], off offset:1536
	s_waitcnt vmcnt(12)
	v_mfma_f32_16x16x32_bf16 v[6:9], v[44:47], v[40:43], v[6:9]
	v_mfma_f32_16x16x32_bf16 v[2:5], v[48:51], v[40:43], v[2:5]
	global_load_dwordx4 v[40:43], v[38:39], off offset:1600
	global_load_dwordx4 v[44:47], v[20:21], off offset:1600
	global_load_dwordx4 v[48:51], v[22:23], off offset:1600
	s_waitcnt vmcnt(12)
	v_mfma_f32_16x16x32_bf16 v[6:9], v[62:65], v[52:55], v[6:9]
	v_mfma_f32_16x16x32_bf16 v[2:5], v[70:73], v[52:55], v[2:5]
	global_load_dwordx4 v[52:55], v[38:39], off offset:1664
	global_load_dwordx4 v[62:65], v[20:21], off offset:1664
	global_load_dwordx4 v[70:73], v[22:23], off offset:1664
	s_waitcnt vmcnt(12)
	v_mfma_f32_16x16x32_bf16 v[6:9], v[86:89], v[82:85], v[6:9]
	v_mfma_f32_16x16x32_bf16 v[2:5], v[94:97], v[82:85], v[2:5]
	global_load_dwordx4 v[82:85], v[38:39], off offset:1728
	global_load_dwordx4 v[86:89], v[20:21], off offset:1728
	global_load_dwordx4 v[94:97], v[22:23], off offset:1728
	s_waitcnt vmcnt(12)
	v_mfma_f32_16x16x32_bf16 v[6:9], v[130:133], v[102:105], v[6:9]
	v_mfma_f32_16x16x32_bf16 v[2:5], v[134:137], v[102:105], v[2:5]
	global_load_dwordx4 v[102:105], v[38:39], off offset:1792
	global_load_dwordx4 v[130:133], v[20:21], off offset:1792
	global_load_dwordx4 v[134:137], v[22:23], off offset:1792
	s_waitcnt vmcnt(12)
	v_mfma_f32_16x16x32_bf16 v[6:9], v[142:145], v[138:141], v[6:9]
	v_mfma_f32_16x16x32_bf16 v[2:5], v[148:151], v[138:141], v[2:5]
	global_load_dwordx4 v[138:141], v[38:39], off offset:1856
	global_load_dwordx4 v[142:145], v[20:21], off offset:1856
	global_load_dwordx4 v[148:151], v[22:23], off offset:1856
	s_waitcnt vmcnt(12)
	v_mfma_f32_16x16x32_bf16 v[6:9], v[44:47], v[40:43], v[6:9]
	v_mfma_f32_16x16x32_bf16 v[2:5], v[48:51], v[40:43], v[2:5]
	global_load_dwordx4 v[40:43], v[38:39], off offset:1920
	global_load_dwordx4 v[44:47], v[20:21], off offset:1920
	global_load_dwordx4 v[48:51], v[22:23], off offset:1920
	s_waitcnt vmcnt(12)
	v_mfma_f32_16x16x32_bf16 v[6:9], v[62:65], v[52:55], v[6:9]
	v_mfma_f32_16x16x32_bf16 v[2:5], v[70:73], v[52:55], v[2:5]
	global_load_dwordx4 v[52:55], v[38:39], off offset:1984
	global_load_dwordx4 v[62:65], v[20:21], off offset:1984
	global_load_dwordx4 v[70:73], v[22:23], off offset:1984
	s_waitcnt vmcnt(12)
	v_mfma_f32_16x16x32_bf16 v[6:9], v[86:89], v[82:85], v[6:9]
	v_mfma_f32_16x16x32_bf16 v[2:5], v[94:97], v[82:85], v[2:5]
	s_waitcnt vmcnt(9)
	v_mfma_f32_16x16x32_bf16 v[6:9], v[130:133], v[102:105], v[6:9]
	v_mfma_f32_16x16x32_bf16 v[2:5], v[134:137], v[102:105], v[2:5]
	s_waitcnt vmcnt(6)
	v_mfma_f32_16x16x32_bf16 v[6:9], v[142:145], v[138:141], v[6:9]
	v_mfma_f32_16x16x32_bf16 v[2:5], v[148:151], v[138:141], v[2:5]
	s_waitcnt vmcnt(3)
	v_mfma_f32_16x16x32_bf16 v[6:9], v[44:47], v[40:43], v[6:9]
	v_mfma_f32_16x16x32_bf16 v[2:5], v[48:51], v[40:43], v[2:5]
	s_waitcnt vmcnt(0)
	v_mfma_f32_16x16x32_bf16 v[6:9], v[62:65], v[52:55], v[6:9]
	v_mfma_f32_16x16x32_bf16 v[2:5], v[70:73], v[52:55], v[2:5]
	s_nop 0
	s_nop 4
	v_mul_f32_e32 v1, 0xbfb8aa3b, v6
	v_rndne_f32_e32 v15, v1
	v_sub_f32_e32 v18, v1, v15
	v_fma_f32 v1, v6, s83, -v1
	v_fmac_f32_e32 v1, 0xb2a5705f, v6
	v_add_f32_e32 v1, v18, v1
	v_cvt_i32_f32_e32 v15, v15
	v_exp_f32_e32 v1, v1
	v_cmp_nlt_f32_e32 vcc, s92, v6
	v_lshl_or_b32 v18, s3, 4, v24
	v_ldexp_f32 v1, v1, v15
	v_cndmask_b32_e32 v1, 0, v1, vcc
	v_cmp_ngt_f32_e32 vcc, s93, v6
	s_nop 1
	v_cndmask_b32_e32 v1, v230, v1, vcc
	v_add_f32_e32 v1, 1.0, v1
	v_div_scale_f32 v6, s[4:5], v1, v1, 1.0
	v_rcp_f32_e32 v15, v6
	s_movk_i32 s4, 0x60
	v_fma_f32 v19, -v6, v15, 1.0
	v_fmac_f32_e32 v15, v19, v15
	v_div_scale_f32 v19, vcc, 1.0, v1, 1.0
	v_mul_f32_e32 v20, v19, v15
	v_fma_f32 v21, -v6, v20, v19
	v_fmac_f32_e32 v20, v21, v15
	v_fma_f32 v6, -v6, v20, v19
	v_div_fmas_f32 v6, v6, v15, v20
	v_div_fixup_f32 v1, v6, v1, 1.0
	v_mad_i64_i32 v[18:19], s[4:5], v18, s4, v[10:11]
	v_mov_b64_e32 v[20:21], 4
	global_store_dword v[18:19], v1, off
	s_and_saveexec_b64 s[14:15], s[0:1]
	s_cbranch_execz .LBB0_1343
; __device__ __forceinline__ float sigmoidf_(float x) { return 1.f / (1.f + expf(-x)); }
; __device__ __forceinline__ void gates_tiles(const Frame& F, int l, int wg0) {
;     ...
;         float* ng = (float*)(F.ws + WS_NG) + (size_t)(16 * rt + fr) * 24;
; #pragma unroll
;         for (int j = 0; j < 4; ++j) { ng[4 * fq + j] = sigmoidf_(a0[j]); if (fq < 2) ng[16 + 4 * fq + j] = sigmoidf_(a1[j]); }
	v_mul_f32_e32 v1, 0xbfb8aa3b, v2
	v_rndne_f32_e32 v6, v1
	v_sub_f32_e32 v15, v1, v6
	v_fma_f32 v1, v2, s83, -v1
	v_fmac_f32_e32 v1, 0xb2a5705f, v2
	v_add_f32_e32 v1, v15, v1
	v_exp_f32_e32 v1, v1
	v_cvt_i32_f32_e32 v6, v6
	v_cmp_nlt_f32_e32 vcc, s92, v2
	v_ldexp_f32 v1, v1, v6
	s_nop 0
	v_cndmask_b32_e32 v1, 0, v1, vcc
	v_cmp_ngt_f32_e32 vcc, s93, v2
	s_nop 1
	v_cndmask_b32_e32 v1, v230, v1, vcc
	v_add_f32_e32 v1, 1.0, v1
	v_div_scale_f32 v2, s[4:5], v1, v1, 1.0
	v_rcp_f32_e32 v6, v2
	s_nop 0
	v_fma_f32 v15, -v2, v6, 1.0
	v_fmac_f32_e32 v6, v15, v6
	v_div_scale_f32 v15, vcc, 1.0, v1, 1.0
	v_mul_f32_e32 v20, v15, v6
	v_fma_f32 v21, -v2, v20, v15
	v_fmac_f32_e32 v20, v21, v6
	v_fma_f32 v2, -v2, v20, v15
	v_div_fmas_f32 v2, v2, v6, v20
	v_div_fixup_f32 v1, v2, v1, 1.0
	global_store_dword v[18:19], v1, off offset:64
	v_mul_f32_e32 v1, 0xbfb8aa3b, v7
	v_rndne_f32_e32 v2, v1
	v_sub_f32_e32 v6, v1, v2
	v_fma_f32 v1, v7, s83, -v1
	v_fmac_f32_e32 v1, 0xb2a5705f, v7
	v_add_f32_e32 v1, v6, v1
	v_exp_f32_e32 v1, v1
	v_cvt_i32_f32_e32 v2, v2
	v_cmp_nlt_f32_e32 vcc, s92, v7
	v_ldexp_f32 v1, v1, v2
	s_nop 0
	v_cndmask_b32_e32 v1, 0, v1, vcc
	v_cmp_ngt_f32_e32 vcc, s93, v7
	s_nop 1
	v_cndmask_b32_e32 v1, v230, v1, vcc
	v_add_f32_e32 v1, 1.0, v1
	v_div_scale_f32 v2, s[4:5], v1, v1, 1.0
	v_rcp_f32_e32 v6, v2
	s_nop 0
	v_fma_f32 v7, -v2, v6, 1.0
	v_fmac_f32_e32 v6, v7, v6
	v_div_scale_f32 v7, vcc, 1.0, v1, 1.0
	v_mul_f32_e32 v15, v7, v6
	v_fma_f32 v20, -v2, v15, v7
	v_fmac_f32_e32 v15, v20, v6
	v_fma_f32 v2, -v2, v15, v7
	v_div_fmas_f32 v2, v2, v6, v15
	v_div_fixup_f32 v1, v2, v1, 1.0
	v_mov_b64_e32 v[20:21], 0x44
	v_mov_b32_e32 v7, v3
	global_store_dword v[18:19], v1, off offset:4
